# HGRN pass C: loop-invariant norm-gain vector loaded once before the item loop instead of twice per item
# speedup vs baseline: 1.0075x; 1.0006x over previous
; DI void hgC_load(unsigned char* ws, int item, unsigned (&lf)[16], unsigned (&qv)[16], u32x4 (&ivw)[2]) {
;     const int tid = threadIdx.x, b = item >> 10, h = (item >> 6) & 15, c = item & 63, t0 = b * SEQ + c * 64, kp = tid & 63, tq = tid >> 6;
;     const bf16_t* LOGF = (const bf16_t*)(ws + WS_LOGF);
;     const bf16_t* Q2 = (const bf16_t*)(ws + WS_Q2);
; #pragma unroll
;     for (int i = 0; i < 8; ++i) { const size_t o = (size_t)(t0 + tq * 8 + i) * DM + h * 128 + 2 * kp; lf[i] = *(const unsigned*)(LOGF + o); qv[i] = *(const unsigned*)(Q2 + o); }
;     hg_iv_load((const bf16_t*)(ws + WS_IV), item, ivw);
; __global__ void __launch_bounds__(512, 2) fwd_kernel(Args a) {
;     ...
;     if (IN(9)) {
;         __syncthreads();
;         int it = bx; unsigned lfa[16], qva[16]; u32x4 iva[2];
;         if (it < 2048) hgC_load(ws, it, lfa, qva, iva);
.LBB0_1108:
	s_cmp_lt_i32 s84, 10
	s_cselect_b64 s[4:5], -1, 0
	s_and_b64 s[0:1], s[4:5], s[0:1]
	s_andn2_b64 vcc, exec, s[0:1]
	s_cbranch_vccnz .LBB0_1124
	s_cmpk_gt_i32 s2, 0x7ff
	s_waitcnt vmcnt(0) lgkmcnt(0)
	s_barrier
	s_cbranch_scc1 .LBB0_1124
	s_lshl_b32 s3, s2, 2
	s_lshl_b32 s4, s2, 6
	s_and_b32 s3, s3, 0xfffff000
	s_and_b32 s4, s4, 0xfc0
	s_add_u32 s64, s82, 0x8c80000
	s_addc_u32 s65, s83, 0
	s_add_u32 s66, s82, 0x4c80000
	v_lshrrev_b32_e32 v18, 3, v253
	s_addc_u32 s67, s83, 0
	v_and_b32_e32 v89, 0x78, v18
	s_or_b32 s3, s3, s4
	v_add_u32_e32 v0, s3, v89
	s_lshl_b32 s3, s2, 1
	v_lshlrev_b32_e32 v1, 1, v253
	s_and_b32 s3, s3, 0x780
	v_and_b32_e32 v98, 0x7e, v1
	v_or_b32_e32 v4, s3, v98
	v_ashrrev_i32_e32 v1, 31, v0
	v_or_b32_e32 v6, 1, v0
	v_or_b32_e32 v10, 2, v0
	v_or_b32_e32 v14, 3, v0
	v_lshlrev_b64 v[2:3], 12, v[0:1]
	v_lshlrev_b32_e32 v19, 1, v4
	v_ashrrev_i32_e32 v7, 31, v6
	v_ashrrev_i32_e32 v11, 31, v10
	v_ashrrev_i32_e32 v15, 31, v14
	v_or_b32_e32 v2, v2, v19
	v_lshlrev_b64 v[6:7], 12, v[6:7]
	v_lshlrev_b64 v[10:11], 12, v[10:11]
	v_lshlrev_b64 v[14:15], 12, v[14:15]
	v_lshl_add_u64 v[4:5], s[64:65], 0, v[2:3]
	v_lshl_add_u64 v[2:3], s[66:67], 0, v[2:3]
	v_or_b32_e32 v6, v6, v19
	v_or_b32_e32 v10, v10, v19
	v_or_b32_e32 v14, v14, v19
	v_lshl_add_u64 v[8:9], s[64:65], 0, v[6:7]
	v_lshl_add_u64 v[6:7], s[66:67], 0, v[6:7]
	v_lshl_add_u64 v[12:13], s[64:65], 0, v[10:11]
	v_lshl_add_u64 v[10:11], s[66:67], 0, v[10:11]
	v_lshl_add_u64 v[16:17], s[64:65], 0, v[14:15]
	v_lshl_add_u64 v[14:15], s[66:67], 0, v[14:15]
	global_load_dword v48, v[4:5], off
	global_load_dword v31, v[2:3], off
	global_load_dword v30, v[8:9], off
	global_load_dword v29, v[6:7], off
	global_load_dword v28, v[12:13], off
	global_load_dword v27, v[10:11], off
	global_load_dword v26, v[16:17], off
	global_load_dword v24, v[14:15], off
	v_or_b32_e32 v2, 4, v0
	v_ashrrev_i32_e32 v3, 31, v2
	v_or_b32_e32 v6, 5, v0
	v_or_b32_e32 v10, 6, v0
	v_or_b32_e32 v0, 7, v0
	v_lshlrev_b64 v[2:3], 12, v[2:3]
	v_ashrrev_i32_e32 v7, 31, v6
	v_ashrrev_i32_e32 v11, 31, v10
	v_ashrrev_i32_e32 v1, 31, v0
	s_add_u32 s4, s82, 0xcc80000
	v_or_b32_e32 v2, v2, v19
	v_lshlrev_b64 v[6:7], 12, v[6:7]
	v_lshlrev_b64 v[10:11], 12, v[10:11]
	v_lshlrev_b64 v[0:1], 12, v[0:1]
	s_addc_u32 s5, s83, 0
	s_ashr_i32 s3, s2, 31
	v_lshl_add_u64 v[4:5], s[64:65], 0, v[2:3]
	v_or_b32_e32 v6, v6, v19
	v_or_b32_e32 v10, v10, v19
	v_or_b32_e32 v0, v0, v19
	s_lshl_b64 s[6:7], s[2:3], 14
	v_lshl_add_u64 v[2:3], s[66:67], 0, v[2:3]
	v_lshl_add_u64 v[8:9], s[64:65], 0, v[6:7]
	v_lshl_add_u64 v[6:7], s[66:67], 0, v[6:7]
	v_lshl_add_u64 v[12:13], s[64:65], 0, v[10:11]
	v_lshl_add_u64 v[10:11], s[66:67], 0, v[10:11]
	v_lshl_add_u64 v[14:15], s[64:65], 0, v[0:1]
	v_lshl_add_u64 v[0:1], s[66:67], 0, v[0:1]
	global_load_dword v56, v[4:5], off
	global_load_dword v53, v[2:3], off
	global_load_dword v52, v[8:9], off
	global_load_dword v51, v[6:7], off
	global_load_dword v25, v[12:13], off
	global_load_dword v71, v[10:11], off
	global_load_dword v50, v[14:15], off
	global_load_dword v70, v[0:1], off
	s_add_u32 s6, s4, s6
	s_addc_u32 s7, s5, s7
	v_mov_b32_e32 v81, 0
	v_lshlrev_b32_e32 v80, 4, v253
	v_lshl_add_u64 v[0:1], s[6:7], 0, v[80:81]
	s_movk_i32 s3, 0x2000
	v_add_co_u32_e32 v10, vcc, s3, v0
	v_lshlrev_b32_e32 v8, 3, v253
	s_nop 0
	v_addc_co_u32_e32 v11, vcc, 0, v1, vcc
	global_load_dwordx4 v[4:7], v80, s[6:7]
	global_load_dwordx4 v[0:3], v[10:11], off
	s_bitcmp1_b32 s86, 1
	s_cselect_b64 s[70:71], -1, 0
	s_add_u32 s73, s82, 0xed00000
	v_and_b32_e32 v10, 0x78, v8
	s_addc_u32 s93, s83, 0
	v_lshlrev_b32_e32 v12, 1, v10
	v_mov_b32_e32 v13, v81
	v_lshl_add_u64 v[82:83], s[4:5], 0, v[80:81]
	s_add_u32 s94, s82, 0x2480000
	v_lshl_add_u64 v[14:15], s[82:83], 0, v[12:13]
	s_mov_b64 s[4:5], 0x400000
	v_lshrrev_b32_e32 v17, 5, v252
	s_addc_u32 s95, s83, 0
	v_lshl_add_u64 v[84:85], v[14:15], 0, s[4:5]
	v_lshlrev_b32_e32 v14, 3, v252
	v_mov_b32_e32 v15, v81
	s_add_i32 s4, 0, 0x11400
	v_mul_u32_u24_e32 v13, 0x90, v18
	v_lshlrev_b32_e32 v18, 2, v17
	v_and_b32_e32 v100, 31, v253
	v_lshl_add_u64 v[86:87], s[24:25], 0, v[14:15]
	v_add_u32_e32 v103, s4, v14
	v_and_b32_e32 v14, 0xf0, v80
	s_add_i32 s20, 0, 0x12800
	v_lshlrev_b32_e32 v108, 4, v17
	v_lshlrev_b32_e32 v110, 3, v17
	v_or_b32_e32 v17, 27, v18
	v_add_u32_e32 v105, s20, v14
	v_add_u32_e32 v109, s20, v108
	v_cmp_gt_u32_e64 s[20:21], v17, v100
	v_or_b32_e32 v17, 26, v18
	v_cmp_gt_u32_e64 s[22:23], v17, v100
	v_or_b32_e32 v17, 25, v18
	v_cmp_gt_u32_e64 s[24:25], v17, v100
	v_or_b32_e32 v17, 24, v18
	v_cmp_gt_u32_e64 s[26:27], v17, v100
	v_or_b32_e32 v17, 19, v18
	v_cmp_gt_u32_e64 s[28:29], v17, v100
	v_or_b32_e32 v17, 18, v18
	v_cmp_gt_u32_e64 s[30:31], v17, v100
	v_or_b32_e32 v17, 17, v18
	v_cmp_gt_u32_e64 s[34:35], v17, v100
	v_or_b32_e32 v17, 16, v18
	v_cmp_gt_u32_e64 s[36:37], v17, v100
	v_or_b32_e32 v17, 11, v18
	v_cmp_gt_u32_e64 s[38:39], v17, v100
	v_or_b32_e32 v17, 10, v18
	v_cmp_gt_u32_e64 s[40:41], v17, v100
	v_or_b32_e32 v17, 9, v18
	v_cmp_gt_u32_e64 s[42:43], v17, v100
	v_or_b32_e32 v17, 8, v18
	v_cmp_gt_u32_e64 s[44:45], v17, v100
	v_or_b32_e32 v17, 3, v18
	v_cmp_gt_u32_e64 s[46:47], v17, v100
	v_or_b32_e32 v17, 2, v18
	v_cmp_gt_u32_e64 s[48:49], v17, v100
	v_mbcnt_lo_u32_b32 v17, -1, 0
	v_mbcnt_hi_u32_b32 v17, -1, v17
	v_and_b32_e32 v19, 64, v17
	v_add_u32_e32 v9, 0x200, v253
	v_add_u32_e32 v14, 0x600, v253
	v_cmp_lt_u32_e64 s[50:51], v18, v100
	v_cmp_gt_u32_e64 s[52:53], v18, v100
	v_xor_b32_e32 v18, 32, v17
	v_add_u32_e32 v19, 64, v19
	v_add_u32_e32 v112, 0, v12
	v_add_u32_e32 v12, 0, v110
	v_lshrrev_b32_e32 v99, 6, v253
	v_lshrrev_b32_e32 v102, 4, v9
	v_and_b32_e32 v11, 0x70, v80
	v_lshrrev_b32_e32 v9, 3, v9
	v_lshrrev_b32_e32 v14, 4, v14
	v_cmp_lt_i32_e32 vcc, v18, v19
	v_add_u32_e32 v113, 0xcc00, v12
	v_mul_u32_u24_e32 v12, 0x110, v100
	v_lshrrev_b32_e32 v101, 4, v253
	v_add_u32_e32 v11, 0, v11
	v_mul_u32_u24_e32 v9, 0x90, v9
	v_mul_u32_u24_e32 v14, 0x110, v14
	s_movk_i32 s6, 0x7f
	s_movk_i32 s8, 0xbf
	s_movk_i32 s10, 0xff
	s_movk_i32 s12, 0x13f
	s_movk_i32 s14, 0x17f
	s_movk_i32 s16, 0x1bf
	s_movk_i32 s18, 0x1ff
	v_lshl_add_u32 v15, v252, 2, 0
	v_mul_u32_u24_e32 v16, 0x880, v99
	v_cndmask_b32_e32 v17, v17, v18, vcc
	v_lshlrev_b32_e32 v80, 2, v10
	v_add3_u32 v12, v12, v108, 0
	s_waitcnt vmcnt(0)
; #define LAS __attribute__((address_space(3)))
; DI u32x2 pack4(const f32x4 a) { u32x2 w; w.x = pk2(a[0], a[1]); w.y = pk2(a[2], a[3]); return w; }
; DI void hgC_item(LAS unsigned char* lds, unsigned char* ws, unsigned char* ob, int item, const float* ng, int dummy, const unsigned (&lfr)[16], const unsigned (&qvr)[16], const u32x4 (&ivw)[2], const float* lbp) {
;     ...
;     {
;         const int t = tb * 32 + r;
;         const float tots = (red[t] + red[64 + t]) + (red[128 + t] + red[192 + t]);
;         const float rs = rsqrtf(tots * (1.f / 128.f) + EPS_);
;         LAS unsigned char* OB = QI;
; #pragma unroll
;         for (int g4 = 0; g4 < 4; ++g4) {
;             const int v0 = 32 * vb + 8 * g4 + 4 * h2;
;             const f32x4 o = {acc[4 * g4 + 0] * rs, acc[4 * g4 + 1] * rs, acc[4 * g4 + 2] * rs, acc[4 * g4 + 3] * rs};
;             *(LAS u32x2*)(OB + t * HROW + v0 * 2) = pack4(o);
;         }
;     }
;     __syncthreads();
; #pragma unroll
;     for (int j = 0; j < 2; ++j) {
;         const int id = tid + 512 * j, t = id >> 4, c8 = (id & 15) * 8;
;         const u32x4 ov = *(const LAS u32x4*)(QI + t * HROW + c8 * 2);
;         const f32x4 n0 = *(const f32x4*)(ng + c8), n1 = *(const f32x4*)(ng + c8 + 4);
	v_mov_b64_e32 v[38:39], v[2:3]
	v_mov_b64_e32 v[34:35], v[6:7]
	s_mov_b32 s69, 0
	v_lshl_add_u32 v104, v99, 9, v103
	s_movk_i32 s96, 0x110
	v_mul_u32_u24_e32 v106, 0x110, v101
	v_mul_u32_u24_e32 v107, 0x110, v102
	v_cmp_gt_u32_e64 s[4:5], 64, v253
	v_cmp_lt_u32_e64 s[6:7], s6, v253
	v_cmp_lt_u32_e64 s[8:9], s8, v253
	v_cmp_lt_u32_e64 s[10:11], s10, v253
	v_cmp_lt_u32_e64 s[12:13], s12, v253
	v_cmp_lt_u32_e64 s[14:15], s14, v253
	v_cmp_lt_u32_e64 s[16:17], s16, v253
	v_cmp_lt_u32_e64 s[18:19], s18, v253
	v_add_u32_e32 v88, 0, v108
	v_lshlrev_b32_e32 v111, 2, v17
	v_cmp_gt_u32_e64 s[54:55], 32, v252
	v_lshl_add_u64 v[90:91], s[74:75], 0, v[80:81]
	v_add_u32_e32 v114, 0x8800, v12
	v_lshlrev_b32_e32 v80, 1, v8
	v_add_u32_e32 v115, v11, v13
	s_mov_b32 s72, 0x3f317218
	v_add_u32_e32 v116, v11, v9
	v_add_u32_e32 v117, v105, v14
	v_add_u32_e32 v118, v15, v16
	v_mov_b32_e32 v119, 0x358637bd
	v_lshlrev_b32_e32 v92, 1, v10
	s_mov_b32 s68, s2
	v_mov_b64_e32 v[36:37], v[0:1]
	v_mov_b64_e32 v[32:33], v[4:5]
	global_load_dwordx4 v[190:193], v[90:91], off
	global_load_dwordx4 v[194:197], v[90:91], off offset:16
	s_branch .LBB0_1112
.LBB0_1111:
	s_waitcnt vmcnt(0)
	s_or_b64 exec, exec, s[90:91]
	v_lshl_add_u32 v16, v136, 2, 0
	v_add_u32_e32 v18, 0x12400, v16
	s_waitcnt lgkmcnt(0)
	s_barrier
	ds_read2st64_b32 v[16:17], v18 offset1:1
	ds_read2st64_b32 v[18:19], v18 offset0:2 offset1:3
	s_mov_b32 s33, 0x800000
	v_add_u32_e32 v28, v112, v107
	v_mov_b32_e32 v50, v134
	s_waitcnt lgkmcnt(1)
	v_mov_b32_e32 v20, v16
	s_waitcnt lgkmcnt(0)
	v_mov_b32_e32 v21, v18
	v_mov_b32_e32 v18, v17
	v_pk_add_f32 v[16:17], v[20:21], v[18:19]
	v_lshlrev_b32_e32 v18, 16, v47
	v_add_f32_e32 v16, v16, v17
	v_fmamk_f32 v16, v16, 0x3c000000, v119
	v_mul_f32_e32 v17, 0x4b800000, v16
	v_cmp_gt_f32_e32 vcc, s33, v16
	s_lshl_b32 s33, s75, 6
	v_and_b32_e32 v19, 0xffff0000, v47
	v_cndmask_b32_e32 v16, v16, v17, vcc
	v_rsq_f32_e32 v16, v16
	v_mul_f32_e32 v23, 0xbfb8aa3b, v18
	v_mul_f32_e32 v24, 0xbfb8aa3b, v19
	v_exp_f32_e32 v30, v23
	v_mul_f32_e32 v17, 0x45800000, v16
	v_cndmask_b32_e32 v16, v16, v17, vcc
	v_add3_u32 v17, v93, s33, v110
	v_pk_mul_f32 v[0:1], v[0:1], v[16:17] op_sel_hi:[1,0]
	v_pk_mul_f32 v[2:3], v[2:3], v[16:17] op_sel_hi:[1,0]
	v_cvt_pk_bf16_f32 v0, v0, v1
	v_cvt_pk_bf16_f32 v1, v2, v3
	v_pk_mul_f32 v[2:3], v[4:5], v[16:17] op_sel_hi:[1,0]
	v_pk_mul_f32 v[4:5], v[6:7], v[16:17] op_sel_hi:[1,0]
	v_cvt_pk_bf16_f32 v2, v2, v3
	v_cvt_pk_bf16_f32 v3, v4, v5
	ds_write2_b64 v17, v[0:1], v[2:3] offset1:2
	v_pk_mul_f32 v[0:1], v[8:9], v[16:17] op_sel_hi:[1,0]
	v_pk_mul_f32 v[2:3], v[10:11], v[16:17] op_sel_hi:[1,0]
	v_cvt_pk_bf16_f32 v0, v0, v1
	v_cvt_pk_bf16_f32 v1, v2, v3
	v_pk_mul_f32 v[2:3], v[12:13], v[16:17] op_sel_hi:[1,0]
	v_pk_mul_f32 v[4:5], v[14:15], v[16:17] op_sel_hi:[1,0]
	v_cvt_pk_bf16_f32 v2, v2, v3
	v_cvt_pk_bf16_f32 v3, v4, v5
	ds_write2_b64 v17, v[0:1], v[2:3] offset0:4 offset1:6
	s_waitcnt lgkmcnt(0)
	s_barrier
; #define LAS __attribute__((address_space(3)))
; DI float siluf_(float x) { return x * frcp(1.f + fexp(-x)); }
; DI u32x4 pack8(const f32x4 a, const f32x4 b) { u32x4 w; w.x = pk2(a[0], a[1]); w.y = pk2(a[2], a[3]); w.z = pk2(b[0], b[1]); w.w = pk2(b[2], b[3]); return w; }
; DI void hgC_item(LAS unsigned char* lds, unsigned char* ws, unsigned char* ob, int item, const float* ng, int dummy, const unsigned (&lfr)[16], const unsigned (&qvr)[16], const u32x4 (&ivw)[2], const float* lbp) {
;     ...
; #pragma unroll
;     for (int j = 0; j < 2; ++j) {
;         const int id = tid + 512 * j, t = id >> 4, c8 = (id & 15) * 8;
;         const u32x4 ov = *(const LAS u32x4*)(QI + t * HROW + c8 * 2);
;         const f32x4 n0 = *(const f32x4*)(ng + c8), n1 = *(const f32x4*)(ng + c8 + 4);
;         const u32x4 z = gz[j];
;         f32x4 o0, o1;
;         o0[0] = bflo(ov.x) * n0[0] * siluf_(bflo(z.x)); o0[1] = bfhi(ov.x) * n0[1] * siluf_(bfhi(z.x));
;         o0[2] = bflo(ov.y) * n0[2] * siluf_(bflo(z.y)); o0[3] = bfhi(ov.y) * n0[3] * siluf_(bfhi(z.y));
;         o1[0] = bflo(ov.z) * n1[0] * siluf_(bflo(z.z)); o1[1] = bfhi(ov.z) * n1[1] * siluf_(bfhi(z.z));
;         o1[2] = bflo(ov.w) * n1[2] * siluf_(bflo(z.w)); o1[3] = bfhi(ov.w) * n1[3] * siluf_(bfhi(z.w));
;         *(u32x4*)(MIX2 + (size_t)(t0 + t) * DM + h * 128 + c8) = pack8(o0, o1);
;     }
;     __syncthreads();
	s_nop 1
	v_mov_b32_e32 v0, v190
	v_mov_b32_e32 v1, v191
	v_mov_b32_e32 v2, v192
	v_mov_b32_e32 v3, v193
	v_mov_b32_e32 v4, v194
	v_mov_b32_e32 v5, v195
	v_mov_b32_e32 v6, v196
	v_mov_b32_e32 v7, v197
	v_lshlrev_b32_e32 v12, 16, v44
	v_and_b32_e32 v13, 0xffff0000, v44
	v_lshlrev_b32_e32 v14, 16, v45
	v_lshlrev_b32_e32 v16, 16, v46
	v_and_b32_e32 v17, 0xffff0000, v46
	v_mul_f32_e32 v9, 0xbfb8aa3b, v12
	v_mul_f32_e32 v10, 0xbfb8aa3b, v13
	v_mul_f32_e32 v11, 0xbfb8aa3b, v14
	v_mul_f32_e32 v21, 0xbfb8aa3b, v16
	v_mul_f32_e32 v22, 0xbfb8aa3b, v17
	v_exp_f32_e32 v9, v9
	v_exp_f32_e32 v10, v10
	v_exp_f32_e32 v11, v11
	v_exp_f32_e32 v26, v21
	v_exp_f32_e32 v22, v22
	v_add_u32_e32 v8, v112, v106
	v_and_b32_e32 v15, 0xffff0000, v45
	v_add_f32_e32 v9, 1.0, v9
	v_add_f32_e32 v10, 1.0, v10
	v_add_f32_e32 v11, 1.0, v11
	v_mul_f32_e32 v20, 0xbfb8aa3b, v15
	v_exp_f32_e32 v31, v24
	v_add_f32_e32 v26, 1.0, v26
	v_add_f32_e32 v27, 1.0, v22
	v_rcp_f32_e32 v22, v9
	v_rcp_f32_e32 v23, v10
	v_rcp_f32_e32 v24, v11
	ds_read_b128 v[8:11], v8
	v_exp_f32_e32 v25, v20
	v_rcp_f32_e32 v26, v26
	v_rcp_f32_e32 v27, v27
	s_lshl_b32 s33, s97, 1
	v_add_f32_e32 v25, 1.0, v25
	v_rcp_f32_e32 v25, v25
	v_pk_mul_f32 v[16:17], v[26:27], v[16:17]
	s_waitcnt lgkmcnt(0)
	v_lshlrev_b32_e32 v26, 16, v8
	v_and_b32_e32 v27, 0xffff0000, v8
	v_lshlrev_b32_e32 v8, 16, v9
	v_and_b32_e32 v9, 0xffff0000, v9
	s_add_u32 s56, s86, s33
	v_pk_mul_f32 v[22:23], v[22:23], v[12:13]
	v_pk_mul_f32 v[24:25], v[24:25], v[14:15]
	ds_read_b128 v[12:15], v28
	v_lshlrev_b32_e32 v28, 16, v10
	v_and_b32_e32 v29, 0xffff0000, v10
	v_lshlrev_b32_e32 v10, 16, v11
	v_and_b32_e32 v11, 0xffff0000, v11
	v_mov_b32_e32 v93, v81
	s_addc_u32 s57, s87, 0
	v_lshl_add_u64 v[20:21], s[56:57], 0, v[92:93]
	s_andn2_b64 vcc, exec, s[76:77]
	v_mov_b32_e32 v52, v130
	v_mov_b32_e32 v56, v128
	v_mov_b32_e32 v48, v120
	v_mov_b32_e32 v70, v135
	v_mov_b32_e32 v71, v133
	v_mov_b32_e32 v51, v131
	v_mov_b32_e32 v53, v129
	s_mov_b32 s68, s74
	s_nop 0
	v_pk_mul_f32 v[2:3], v[2:3], v[8:9]
	v_add_f32_e32 v8, 1.0, v30
	v_add_f32_e32 v9, 1.0, v31
	v_rcp_f32_e32 v8, v8
	v_rcp_f32_e32 v9, v9
	v_pk_mul_f32 v[0:1], v[0:1], v[26:27]
	s_nop 0
	v_pk_mul_f32 v[4:5], v[4:5], v[28:29]
	v_pk_mul_f32 v[6:7], v[6:7], v[10:11]
	v_pk_mul_f32 v[8:9], v[8:9], v[18:19]
	v_pk_mul_f32 v[0:1], v[22:23], v[0:1]
	v_pk_mul_f32 v[2:3], v[24:25], v[2:3]
	v_pk_mul_f32 v[4:5], v[16:17], v[4:5]
	v_pk_mul_f32 v[6:7], v[8:9], v[6:7]
	v_cvt_pk_bf16_f32 v0, v0, v1
	v_cvt_pk_bf16_f32 v1, v2, v3
	v_cvt_pk_bf16_f32 v2, v4, v5
	v_cvt_pk_bf16_f32 v3, v6, v7
	v_lshl_add_u64 v[4:5], v[20:21], 0, v[96:97]
	global_store_dwordx4 v[4:5], v[0:3], off
	s_nop 1
	v_mov_b32_e32 v0, v190
	v_mov_b32_e32 v1, v191
	v_mov_b32_e32 v2, v192
	v_mov_b32_e32 v3, v193
	s_nop 0
	v_mov_b32_e32 v4, v194
	v_mov_b32_e32 v5, v195
	v_mov_b32_e32 v6, v196
	v_mov_b32_e32 v7, v197
	v_lshlrev_b32_e32 v8, 16, v40
	v_and_b32_e32 v9, 0xffff0000, v40
	v_lshlrev_b32_e32 v10, 16, v41
	v_and_b32_e32 v11, 0xffff0000, v41
	v_lshlrev_b32_e32 v16, 16, v42
	v_and_b32_e32 v17, 0xffff0000, v42
	v_lshlrev_b32_e32 v18, 16, v43
	v_and_b32_e32 v19, 0xffff0000, v43
	v_mul_f32_e32 v22, 0xbfb8aa3b, v8
	v_mul_f32_e32 v23, 0xbfb8aa3b, v9
	v_mul_f32_e32 v24, 0xbfb8aa3b, v10
	v_mul_f32_e32 v25, 0xbfb8aa3b, v11
	v_mul_f32_e32 v26, 0xbfb8aa3b, v16
	v_mul_f32_e32 v27, 0xbfb8aa3b, v17
	v_mul_f32_e32 v28, 0xbfb8aa3b, v18
	v_mul_f32_e32 v29, 0xbfb8aa3b, v19
	v_exp_f32_e32 v22, v22
	v_exp_f32_e32 v23, v23
	v_exp_f32_e32 v24, v24
	v_exp_f32_e32 v25, v25
	v_exp_f32_e32 v26, v26
	v_exp_f32_e32 v27, v27
	v_exp_f32_e32 v28, v28
	v_exp_f32_e32 v29, v29
	v_add_f32_e32 v22, 1.0, v22
	v_add_f32_e32 v23, 1.0, v23
	v_add_f32_e32 v24, 1.0, v24
	v_add_f32_e32 v25, 1.0, v25
	v_add_f32_e32 v26, 1.0, v26
	v_add_f32_e32 v27, 1.0, v27
	v_add_f32_e32 v28, 1.0, v28
	v_add_f32_e32 v29, 1.0, v29
	v_rcp_f32_e32 v22, v22
	v_rcp_f32_e32 v23, v23
	v_rcp_f32_e32 v24, v24
	v_rcp_f32_e32 v25, v25
	v_rcp_f32_e32 v26, v26
	v_rcp_f32_e32 v27, v27
	v_rcp_f32_e32 v28, v28
	v_rcp_f32_e32 v29, v29
	v_pk_mul_f32 v[8:9], v[22:23], v[8:9]
	v_pk_mul_f32 v[10:11], v[24:25], v[10:11]
	s_waitcnt lgkmcnt(0)
	v_lshlrev_b32_e32 v22, 16, v12
	v_and_b32_e32 v23, 0xffff0000, v12
	v_lshlrev_b32_e32 v12, 16, v13
	v_and_b32_e32 v13, 0xffff0000, v13
	v_lshlrev_b32_e32 v24, 16, v14
	v_and_b32_e32 v25, 0xffff0000, v14
	v_lshlrev_b32_e32 v14, 16, v15
	v_and_b32_e32 v15, 0xffff0000, v15
	v_pk_mul_f32 v[16:17], v[26:27], v[16:17]
	v_pk_mul_f32 v[18:19], v[28:29], v[18:19]
	v_lshl_add_u64 v[20:21], v[20:21], 0, v[94:95]
	v_mov_b32_e32 v26, v126
	v_mov_b32_e32 v28, v124
	v_mov_b32_e32 v30, v122
	v_mov_b32_e32 v27, v125
	v_mov_b32_e32 v29, v123
	v_mov_b32_e32 v31, v121
	s_nop 0
	v_pk_mul_f32 v[0:1], v[0:1], v[22:23]
	v_pk_mul_f32 v[2:3], v[2:3], v[12:13]
	s_nop 0
	v_pk_mul_f32 v[4:5], v[4:5], v[24:25]
	v_pk_mul_f32 v[6:7], v[6:7], v[14:15]
	v_pk_mul_f32 v[0:1], v[8:9], v[0:1]
	v_pk_mul_f32 v[2:3], v[10:11], v[2:3]
	v_pk_mul_f32 v[4:5], v[16:17], v[4:5]
	v_pk_mul_f32 v[6:7], v[18:19], v[6:7]
	v_cvt_pk_bf16_f32 v0, v0, v1
	v_cvt_pk_bf16_f32 v1, v2, v3
	v_cvt_pk_bf16_f32 v2, v4, v5
	v_cvt_pk_bf16_f32 v3, v6, v7
	global_store_dwordx4 v[20:21], v[0:3], off
	v_mov_b64_e32 v[4:5], v[32:33]
	v_mov_b32_e32 v25, v132
	v_mov_b64_e32 v[0:1], v[36:37]
	v_mov_b32_e32 v24, v127
	v_mov_b64_e32 v[6:7], v[34:35]
	v_mov_b64_e32 v[2:3], v[38:39]
	s_barrier
	s_cbranch_vccz .LBB0_1124
